# mixer-A parked pass-0 result: lane-coalesced private layout + read-back prefetched after the tile loop
# speedup vs baseline: 1.0105x; 1.0105x over previous
; template <int PM> DI void attn_phase(const Params& p, int l, char* smem, int* s_item, int wv, int cidx) {
;     ...
;     int qoff, koff, voff;
;     if (mixer == 0) { qoff = head * 128; koff = 512 + head * 128; voff = 1024 + head * 128; }
;     else if (mixer == 1) { qoff = 1536 + head * 128; koff = 2048 + (head >> 1) * 128; voff = 2304 + (head >> 1) * 128; }
;     else if (mixer == 2) { qoff = 2560 + head * 128; koff = 3072 + head * 128; voff = 3584 + head * 128; }
;     else { qoff = 4096 + head * 128; koff = 4608 + (head >> 1) * 128; voff = 4864 + (head >> 1) * 128; }
;     ...
;     const int npass = (mixer == 0) ? 2 : 1;
;     const bool full_d = (mixer != 0);
;     float* asave = p.asave + (size_t)Rq * 512 + head * 128 + 4 * h;
.LBB0_383:
	s_and_b32 s9, s8, 3
	s_cmp_eq_u32 s86, 0
	s_cselect_b64 s[2:3], -1, 0
	v_writelane_b32 v254, s2, 61
	s_cmp_lg_u32 s86, 0
	s_cselect_b64 s[14:15], -1, 0
	v_writelane_b32 v254, s3, 62
	s_lshl_b32 s20, s9, 7
	v_writelane_b32 v255, s20, 20
	s_mov_b64 s[2:3], -1
	v_writelane_b32 v254, s14, 63
	s_and_b64 vcc, exec, s[14:15]
	s_nop 0
	v_writelane_b32 v255, s15, 0
	s_cbranch_vccz .LBB0_399
	s_cmp_lt_i32 s86, 2
	s_cbranch_scc1 .LBB0_390
	s_cmp_lg_u32 s86, 2
	s_cbranch_scc0 .LBB0_387
	s_lshl_b32 s2, s9, 6
	s_and_b32 s2, s2, 0x80
	s_or_b32 s8, s20, 0x1000
	s_or_b32 s6, s2, 0x1200
	s_or_b32 s10, s2, 0x1300
	s_mov_b64 s[2:3], 0

; template <int PM> DI void attn_phase(const Params& p, int l, char* smem, int* s_item, int wv, int cidx) {
;     ...
;       if (mixer == 0 && pass == 0) {
; #pragma unroll
;         for (int db = 0; db < 4; ++db)
; #pragma unroll
;           for (int g = 0; g < 4; ++g) {
;             f32x4 o;
; #pragma unroll
;             for (int e = 0; e < 4; ++e) o[e] = ov[db][4 * g + e];
;             *(f32x4*)(asave + db * 32 + 8 * g) = o;
;           }
;         continue;
.LBB0_407:
	v_readlane_b32 s0, v255, 20
	s_nop 1
	v_mul_u32_u24_e32 v17, 0x7f0, v240
	v_add_u32_e32 v16, s0, v198
	v_mul_u32_u24_e32 v16, 0x7c, v16
	v_sub_u32_e32 v16, v16, v17
	v_ashrrev_i32_e32 v17, 31, v16
	v_lshl_add_u64 v[18:19], v[16:17], 0, v[206:207]
	s_mov_b64 s[0:1], 0x1000
	global_store_dwordx4 v[18:19], v[2:5], off
	global_store_dwordx4 v[18:19], v[6:9], off offset:1024
	global_store_dwordx4 v[18:19], v[48:51], off offset:2048
	global_store_dwordx4 v[18:19], v[56:59], off offset:3072
	v_lshl_add_u64 v[18:19], v[18:19], 0, s[0:1]
	global_store_dwordx4 v[18:19], v[10:13], off
	global_store_dwordx4 v[18:19], v[52:55], off offset:1024
	global_store_dwordx4 v[18:19], v[64:67], off offset:2048
	global_store_dwordx4 v[18:19], v[72:75], off offset:3072
	v_lshl_add_u64 v[18:19], v[18:19], 0, s[0:1]
	global_store_dwordx4 v[18:19], v[60:63], off
	global_store_dwordx4 v[18:19], v[68:71], off offset:1024
	global_store_dwordx4 v[18:19], v[96:99], off offset:2048
	global_store_dwordx4 v[18:19], v[100:103], off offset:3072
	v_lshl_add_u64 v[18:19], v[18:19], 0, s[0:1]
	global_store_dwordx4 v[18:19], v[76:79], off
	global_store_dwordx4 v[18:19], v[80:83], off offset:1024
	global_store_dwordx4 v[18:19], v[84:87], off offset:2048
	global_store_dwordx4 v[18:19], v[88:91], off offset:3072

; template <int PM> DI void attn_phase(const Params& p, int l, char* smem, int* s_item, int wv, int cidx) {
;     ...
;         const float* ap = asave;
; #pragma unroll
;         for (int db = 0; db < 4; ++db) {
;           asm volatile("" : "+v"(ap), "+v"(ss));
; #pragma unroll
;           for (int g = 0; g < 4; ++g) {
;             const f32x4 sv = *(const f32x4*)(ap + db * 32 + 8 * g);
.LBB0_518:
	s_cmp_eq_u32 s86, 0
	s_cselect_b32 vcc_lo, s91, 0
	s_cmp_lg_u32 vcc_lo, 0
	s_cbranch_scc0 .Lasv_skip
	v_readlane_b32 s0, v255, 20
	s_nop 1
	v_mul_u32_u24_e32 v145, 0x7f0, v240
	v_add_u32_e32 v144, s0, v198
	v_mul_u32_u24_e32 v144, 0x7c, v144
	v_sub_u32_e32 v144, v144, v145
	v_ashrrev_i32_e32 v145, 31, v144
	v_lshl_add_u64 v[146:147], v[144:145], 0, v[206:207]
	s_mov_b64 s[0:1], 0x1000
	global_load_dwordx4 v[16:19], v[146:147], off
	global_load_dwordx4 v[20:23], v[146:147], off offset:1024
	global_load_dwordx4 v[24:27], v[146:147], off offset:2048
	global_load_dwordx4 v[28:31], v[146:147], off offset:3072
	v_lshl_add_u64 v[146:147], v[146:147], 0, s[0:1]
	global_load_dwordx4 v[32:35], v[146:147], off
	global_load_dwordx4 v[36:39], v[146:147], off offset:1024
	global_load_dwordx4 v[40:43], v[146:147], off offset:2048
	global_load_dwordx4 v[44:47], v[146:147], off offset:3072
	v_lshl_add_u64 v[146:147], v[146:147], 0, s[0:1]
	global_load_dwordx4 v[176:179], v[146:147], off
	global_load_dwordx4 v[180:183], v[146:147], off offset:1024
	global_load_dwordx4 v[184:187], v[146:147], off offset:2048
	global_load_dwordx4 v[188:191], v[146:147], off offset:3072
	v_lshl_add_u64 v[146:147], v[146:147], 0, s[0:1]
	global_load_dwordx4 v[192:195], v[146:147], off
	global_load_dwordx4 v[210:213], v[146:147], off offset:1024
	global_load_dwordx4 v[214:217], v[146:147], off offset:2048
	global_load_dwordx4 v[218:221], v[146:147], off offset:3072

; DI float fexp2(float x) { return __builtin_amdgcn_exp2f(x); }
; DI float half_sum(float v) { const auto r = __builtin_amdgcn_permlane32_swap(__float_as_uint(v), __float_as_uint(v), false, false); return __uint_as_float(r[0]) + __uint_as_float(r[1]); }
; template <int PM> DI void attn_phase(const Params& p, int l, char* smem, int* s_item, int wv, int cidx) {
;     ...
;       float lt = half_sum(lsum);
;       if (mixer == 1) lt += fexp2(p.sink[l * 4 + head] * LOG2E - m);
;       const float inv = 1.f / lt;
;       float ov[4][16];
; #pragma unroll
;       for (int db = 0; db < 4; ++db)
; #pragma unroll
;         for (int e = 0; e < 16; ++e) ov[db][e] = Oacc[db][e] * inv;
;       if (mixer == 0 && pass == 0) {
; #pragma unroll
;         for (int db = 0; db < 4; ++db)
; #pragma unroll
;           for (int g = 0; g < 4; ++g) {
;             f32x4 o;
; #pragma unroll
;             for (int e = 0; e < 4; ++e) o[e] = ov[db][4 * g + e];
;             *(f32x4*)(asave + db * 32 + 8 * g) = o;
;           }
;         continue;
;       }
;       float rr = 1.f;
;       if (mixer == 0) {
;         float ss = 0.f;
;         const float* ap = asave;
; #pragma unroll
;         for (int db = 0; db < 4; ++db) {
;           asm volatile("" : "+v"(ap), "+v"(ss));
; #pragma unroll
;           for (int g = 0; g < 4; ++g) {
;             const f32x4 sv = *(const f32x4*)(ap + db * 32 + 8 * g);
; #pragma unroll
;             for (int e = 0; e < 4; ++e) { const float o = sv[e] - lam * ov[db][4 * g + e]; ov[db][4 * g + e] = o; ss += o * o; }
;           }
;         }
;         ss = half_sum(ss);
;         rr = rsqrtf(ss * (1.f / 128.f) + EPSV) * (1.f - lambda_init);
.LBB0_524:
	v_div_scale_f32 v2, s[0:1], v0, v0, 1.0
	v_rcp_f32_e32 v3, v2
	v_div_scale_f32 v4, vcc, 1.0, v0, 1.0
	s_or_b32 s0, s91, s86
	v_fma_f32 v5, -v2, v3, 1.0
	v_fmac_f32_e32 v3, v5, v3
	v_mul_f32_e32 v5, v4, v3
	v_fma_f32 v6, -v2, v5, v4
	v_fmac_f32_e32 v5, v6, v3
	v_fma_f32 v2, -v2, v5, v4
	v_div_fmas_f32 v2, v2, v3, v5
	v_div_fixup_f32 v0, v2, v0, 1.0
	v_pk_mul_f32 v[2:3], v[128:129], v[0:1] op_sel_hi:[1,0]
	v_pk_mul_f32 v[4:5], v[130:131], v[0:1] op_sel_hi:[1,0]
	v_pk_mul_f32 v[6:7], v[132:133], v[0:1] op_sel_hi:[1,0]
	v_pk_mul_f32 v[8:9], v[134:135], v[0:1] op_sel_hi:[1,0]
	v_pk_mul_f32 v[48:49], v[136:137], v[0:1] op_sel_hi:[1,0]
	v_pk_mul_f32 v[50:51], v[138:139], v[0:1] op_sel_hi:[1,0]
	v_pk_mul_f32 v[56:57], v[140:141], v[0:1] op_sel_hi:[1,0]
	v_pk_mul_f32 v[58:59], v[142:143], v[0:1] op_sel_hi:[1,0]
	v_pk_mul_f32 v[10:11], v[112:113], v[0:1] op_sel_hi:[1,0]
	v_pk_mul_f32 v[12:13], v[114:115], v[0:1] op_sel_hi:[1,0]
	v_pk_mul_f32 v[52:53], v[116:117], v[0:1] op_sel_hi:[1,0]
	v_pk_mul_f32 v[54:55], v[118:119], v[0:1] op_sel_hi:[1,0]
	v_pk_mul_f32 v[64:65], v[120:121], v[0:1] op_sel_hi:[1,0]
	v_pk_mul_f32 v[66:67], v[122:123], v[0:1] op_sel_hi:[1,0]
	v_pk_mul_f32 v[72:73], v[124:125], v[0:1] op_sel_hi:[1,0]
	v_pk_mul_f32 v[74:75], v[126:127], v[0:1] op_sel_hi:[1,0]
	v_pk_mul_f32 v[60:61], v[96:97], v[0:1] op_sel_hi:[1,0]
	v_pk_mul_f32 v[62:63], v[98:99], v[0:1] op_sel_hi:[1,0]
	v_pk_mul_f32 v[68:69], v[100:101], v[0:1] op_sel_hi:[1,0]
	v_pk_mul_f32 v[70:71], v[102:103], v[0:1] op_sel_hi:[1,0]
	v_pk_mul_f32 v[96:97], v[104:105], v[0:1] op_sel_hi:[1,0]
	v_pk_mul_f32 v[98:99], v[106:107], v[0:1] op_sel_hi:[1,0]
	v_pk_mul_f32 v[100:101], v[108:109], v[0:1] op_sel_hi:[1,0]
	v_pk_mul_f32 v[102:103], v[110:111], v[0:1] op_sel_hi:[1,0]
	v_pk_mul_f32 v[76:77], v[80:81], v[0:1] op_sel_hi:[1,0]
	v_pk_mul_f32 v[78:79], v[82:83], v[0:1] op_sel_hi:[1,0]
	v_pk_mul_f32 v[80:81], v[84:85], v[0:1] op_sel_hi:[1,0]
	v_pk_mul_f32 v[82:83], v[86:87], v[0:1] op_sel_hi:[1,0]
	v_pk_mul_f32 v[84:85], v[88:89], v[0:1] op_sel_hi:[1,0]
	v_pk_mul_f32 v[86:87], v[90:91], v[0:1] op_sel_hi:[1,0]
	v_pk_mul_f32 v[88:89], v[92:93], v[0:1] op_sel_hi:[1,0]
	s_cmp_lg_u32 s0, 0
	v_pk_mul_f32 v[90:91], v[94:95], v[0:1] op_sel_hi:[1,0]
	s_cbranch_scc0 .LBB0_560
	v_readlane_b32 s0, v254, 61
	v_readlane_b32 s1, v254, 62
	v_mov_b32_e32 v92, 1.0
	s_andn2_b64 vcc, exec, s[0:1]
	v_cndmask_b32_e64 v0, 0, 1, s[0:1]
	v_cmp_ne_u32_e64 s[72:73], 1, v0
	v_mov_b32_e32 v170, 1.0
	v_mov_b64_e32 v[166:167], v[90:91]
	v_mov_b64_e32 v[162:163], v[88:89]
	v_mov_b64_e32 v[154:155], v[86:87]
	v_mov_b64_e32 v[156:157], v[84:85]
	v_mov_b64_e32 v[158:159], v[82:83]
	v_mov_b64_e32 v[160:161], v[80:81]
	v_mov_b64_e32 v[164:165], v[78:79]
	v_mov_b64_e32 v[168:169], v[76:77]
	v_mov_b64_e32 v[150:151], v[102:103]
	v_mov_b64_e32 v[142:143], v[100:101]
	v_mov_b64_e32 v[134:135], v[98:99]
	v_mov_b64_e32 v[136:137], v[96:97]
	v_mov_b64_e32 v[138:139], v[70:71]
	v_mov_b64_e32 v[140:141], v[68:69]
	v_mov_b64_e32 v[148:149], v[62:63]
	v_mov_b64_e32 v[152:153], v[60:61]
	v_mov_b64_e32 v[130:131], v[74:75]
	v_mov_b64_e32 v[126:127], v[72:73]
	v_mov_b64_e32 v[118:119], v[66:67]
	v_mov_b64_e32 v[120:121], v[64:65]
	v_mov_b64_e32 v[122:123], v[54:55]
	v_mov_b64_e32 v[124:125], v[52:53]
	v_mov_b64_e32 v[128:129], v[12:13]
	v_mov_b64_e32 v[132:133], v[10:11]
	v_mov_b64_e32 v[116:117], v[58:59]
	v_mov_b64_e32 v[114:115], v[56:57]
	v_mov_b64_e32 v[14:15], v[50:51]
	v_mov_b64_e32 v[110:111], v[48:49]
	v_mov_b64_e32 v[108:109], v[8:9]
	v_mov_b64_e32 v[112:113], v[6:7]
	v_mov_b64_e32 v[104:105], v[4:5]
	v_mov_b64_e32 v[106:107], v[2:3]
	s_cbranch_vccnz .LBB0_527
	v_mov_b64_e32 v[94:95], v[206:207]
	v_mov_b32_e32 v0, v1
	s_waitcnt vmcnt(0)
	v_mov_b64_e32 v[106:107], v[16:17]
	v_mov_b64_e32 v[108:109], v[18:19]
	v_mov_b64_e32 v[114:115], v[24:25]
	v_mov_b64_e32 v[116:117], v[26:27]
	s_mov_b32 s0, 0x800000
	s_waitcnt vmcnt(0) lgkmcnt(0)
	v_pk_fma_f32 v[104:105], s[4:5], v[4:5], v[108:109] neg_lo:[1,0,0] neg_hi:[1,0,0]
	v_mov_b64_e32 v[108:109], v[20:21]
	v_mov_b64_e32 v[110:111], v[22:23]
	v_pk_fma_f32 v[106:107], s[4:5], v[2:3], v[106:107] neg_lo:[1,0,0] neg_hi:[1,0,0]
	s_waitcnt vmcnt(0) lgkmcnt(0)
	v_pk_fma_f32 v[112:113], s[4:5], v[6:7], v[108:109] neg_lo:[1,0,0] neg_hi:[1,0,0]
	v_pk_mul_f32 v[14:15], v[106:107], v[106:107]
	v_pk_fma_f32 v[108:109], s[4:5], v[8:9], v[110:111] neg_lo:[1,0,0] neg_hi:[1,0,0]
	v_add_f32_e32 v0, v0, v14
	v_add_f32_e32 v0, v15, v0
	v_pk_mul_f32 v[14:15], v[104:105], v[104:105]
	v_pk_fma_f32 v[110:111], s[4:5], v[48:49], v[114:115] neg_lo:[1,0,0] neg_hi:[1,0,0]
	v_add_f32_e32 v0, v14, v0
	v_add_f32_e32 v0, v15, v0
	v_pk_mul_f32 v[14:15], v[112:113], v[112:113]
	s_nop 0
	v_add_f32_e32 v0, v14, v0
	v_add_f32_e32 v0, v15, v0
	v_pk_mul_f32 v[14:15], v[108:109], v[108:109]
	s_nop 0
	v_add_f32_e32 v0, v14, v0
	v_add_f32_e32 v0, v15, v0
	v_pk_mul_f32 v[14:15], v[110:111], v[110:111]
	s_nop 0
	v_add_f32_e32 v0, v14, v0
	v_add_f32_e32 v0, v15, v0
	v_pk_fma_f32 v[14:15], s[4:5], v[50:51], v[116:117] neg_lo:[1,0,0] neg_hi:[1,0,0]
	s_nop 0
	v_pk_mul_f32 v[114:115], v[14:15], v[14:15]
	s_nop 0
	v_add_f32_e32 v0, v114, v0
	v_add_f32_e32 v0, v115, v0
	v_mov_b64_e32 v[114:115], v[28:29]
	v_mov_b64_e32 v[116:117], v[30:31]
	s_waitcnt vmcnt(0) lgkmcnt(0)
	v_pk_fma_f32 v[114:115], s[4:5], v[56:57], v[114:115] neg_lo:[1,0,0] neg_hi:[1,0,0]
	s_nop 0
	v_pk_mul_f32 v[118:119], v[114:115], v[114:115]
	v_pk_fma_f32 v[116:117], s[4:5], v[58:59], v[116:117] neg_lo:[1,0,0] neg_hi:[1,0,0]
	v_add_f32_e32 v0, v118, v0
	v_add_f32_e32 v0, v119, v0
	v_pk_mul_f32 v[118:119], v[116:117], v[116:117]
	s_nop 0
	v_add_f32_e32 v0, v118, v0
	v_add_f32_e32 v0, v119, v0
	v_mov_b64_e32 v[118:119], v[32:33]
	v_mov_b64_e32 v[120:121], v[34:35]
	v_mov_b64_e32 v[134:135], v[40:41]
	v_mov_b64_e32 v[136:137], v[42:43]
	s_waitcnt vmcnt(0) lgkmcnt(0)
; DI float half_sum(float v) { const auto r = __builtin_amdgcn_permlane32_swap(__float_as_uint(v), __float_as_uint(v), false, false); return __uint_as_float(r[0]) + __uint_as_float(r[1]); }
; template <int PM> DI void attn_phase(const Params& p, int l, char* smem, int* s_item, int wv, int cidx) {
;     ...
;       if (mixer == 0) {
;         float ss = 0.f;
;         const float* ap = asave;
; #pragma unroll
;         for (int db = 0; db < 4; ++db) {
;           asm volatile("" : "+v"(ap), "+v"(ss));
; #pragma unroll
;           for (int g = 0; g < 4; ++g) {
;             const f32x4 sv = *(const f32x4*)(ap + db * 32 + 8 * g);
; #pragma unroll
;             for (int e = 0; e < 4; ++e) { const float o = sv[e] - lam * ov[db][4 * g + e]; ov[db][4 * g + e] = o; ss += o * o; }
;           }
;         }
;         ss = half_sum(ss);
;         rr = rsqrtf(ss * (1.f / 128.f) + EPSV) * (1.f - lambda_init);
	v_pk_fma_f32 v[132:133], s[4:5], v[10:11], v[118:119] neg_lo:[1,0,0] neg_hi:[1,0,0]
	s_nop 0
	v_pk_mul_f32 v[118:119], v[132:133], v[132:133]
	v_pk_fma_f32 v[128:129], s[4:5], v[12:13], v[120:121] neg_lo:[1,0,0] neg_hi:[1,0,0]
	v_add_f32_e32 v0, v0, v118
	v_add_f32_e32 v0, v119, v0
	v_pk_mul_f32 v[118:119], v[128:129], v[128:129]
	s_nop 0
	v_add_f32_e32 v0, v118, v0
	v_add_f32_e32 v0, v119, v0
	v_mov_b64_e32 v[118:119], v[36:37]
	v_mov_b64_e32 v[120:121], v[38:39]
	s_waitcnt vmcnt(0) lgkmcnt(0)
	v_pk_fma_f32 v[124:125], s[4:5], v[52:53], v[118:119] neg_lo:[1,0,0] neg_hi:[1,0,0]
	s_nop 0
	v_pk_mul_f32 v[118:119], v[124:125], v[124:125]
	v_pk_fma_f32 v[122:123], s[4:5], v[54:55], v[120:121] neg_lo:[1,0,0] neg_hi:[1,0,0]
	v_add_f32_e32 v0, v118, v0
	v_add_f32_e32 v0, v119, v0
	v_pk_mul_f32 v[118:119], v[122:123], v[122:123]
	v_pk_fma_f32 v[120:121], s[4:5], v[64:65], v[134:135] neg_lo:[1,0,0] neg_hi:[1,0,0]
	v_add_f32_e32 v0, v118, v0
	v_add_f32_e32 v0, v119, v0
	v_pk_mul_f32 v[118:119], v[120:121], v[120:121]
	s_nop 0
	v_add_f32_e32 v0, v118, v0
	v_add_f32_e32 v0, v119, v0
	v_pk_fma_f32 v[118:119], s[4:5], v[66:67], v[136:137] neg_lo:[1,0,0] neg_hi:[1,0,0]
	v_mov_b64_e32 v[134:135], v[44:45]
	v_mov_b64_e32 v[136:137], v[46:47]
	v_pk_mul_f32 v[126:127], v[118:119], v[118:119]
	s_nop 0
	v_add_f32_e32 v0, v126, v0
	v_add_f32_e32 v0, v127, v0
	s_waitcnt vmcnt(0) lgkmcnt(0)
	v_pk_fma_f32 v[126:127], s[4:5], v[72:73], v[134:135] neg_lo:[1,0,0] neg_hi:[1,0,0]
	s_nop 0
	v_pk_mul_f32 v[130:131], v[126:127], v[126:127]
	s_nop 0
	v_add_f32_e32 v0, v130, v0
	v_add_f32_e32 v0, v131, v0
	v_pk_fma_f32 v[130:131], s[4:5], v[74:75], v[136:137] neg_lo:[1,0,0] neg_hi:[1,0,0]
	s_nop 0
	v_pk_mul_f32 v[134:135], v[130:131], v[130:131]
	s_nop 0
	v_add_f32_e32 v0, v134, v0
	v_add_f32_e32 v0, v135, v0
	v_mov_b64_e32 v[134:135], v[176:177]
	v_mov_b64_e32 v[136:137], v[178:179]
	v_mov_b64_e32 v[154:155], v[184:185]
	v_mov_b64_e32 v[156:157], v[186:187]
	s_waitcnt vmcnt(0) lgkmcnt(0)
	v_pk_fma_f32 v[152:153], s[4:5], v[60:61], v[134:135] neg_lo:[1,0,0] neg_hi:[1,0,0]
	s_nop 0
	v_pk_mul_f32 v[134:135], v[152:153], v[152:153]
	v_pk_fma_f32 v[148:149], s[4:5], v[62:63], v[136:137] neg_lo:[1,0,0] neg_hi:[1,0,0]
	v_add_f32_e32 v0, v0, v134
	v_add_f32_e32 v0, v135, v0
	v_pk_mul_f32 v[134:135], v[148:149], v[148:149]
	s_nop 0
	v_add_f32_e32 v0, v134, v0
	v_add_f32_e32 v0, v135, v0
	v_mov_b64_e32 v[134:135], v[180:181]
	v_mov_b64_e32 v[136:137], v[182:183]
	s_waitcnt vmcnt(0) lgkmcnt(0)
	v_pk_fma_f32 v[140:141], s[4:5], v[68:69], v[134:135] neg_lo:[1,0,0] neg_hi:[1,0,0]
	s_nop 0
	v_pk_mul_f32 v[134:135], v[140:141], v[140:141]
	v_pk_fma_f32 v[138:139], s[4:5], v[70:71], v[136:137] neg_lo:[1,0,0] neg_hi:[1,0,0]
	v_add_f32_e32 v0, v134, v0
	v_add_f32_e32 v0, v135, v0
	v_pk_mul_f32 v[134:135], v[138:139], v[138:139]
	v_pk_fma_f32 v[136:137], s[4:5], v[96:97], v[154:155] neg_lo:[1,0,0] neg_hi:[1,0,0]
	v_add_f32_e32 v0, v134, v0
	v_add_f32_e32 v0, v135, v0
	v_pk_mul_f32 v[134:135], v[136:137], v[136:137]
	s_nop 0
	v_add_f32_e32 v0, v134, v0
	v_add_f32_e32 v0, v135, v0
	v_pk_fma_f32 v[134:135], s[4:5], v[98:99], v[156:157] neg_lo:[1,0,0] neg_hi:[1,0,0]
	v_mov_b64_e32 v[154:155], v[188:189]
	v_mov_b64_e32 v[156:157], v[190:191]
	v_pk_mul_f32 v[142:143], v[134:135], v[134:135]
	s_nop 0
	v_add_f32_e32 v0, v142, v0
	v_add_f32_e32 v0, v143, v0
	s_waitcnt vmcnt(0) lgkmcnt(0)
	v_pk_fma_f32 v[142:143], s[4:5], v[100:101], v[154:155] neg_lo:[1,0,0] neg_hi:[1,0,0]
	s_nop 0
	v_pk_mul_f32 v[150:151], v[142:143], v[142:143]
	s_nop 0
	v_add_f32_e32 v0, v150, v0
	v_add_f32_e32 v0, v151, v0
	v_pk_fma_f32 v[150:151], s[4:5], v[102:103], v[156:157] neg_lo:[1,0,0] neg_hi:[1,0,0]
	s_nop 0
	v_pk_mul_f32 v[154:155], v[150:151], v[150:151]
	s_nop 0
	v_add_f32_e32 v0, v154, v0
	v_add_f32_e32 v0, v155, v0
	v_mov_b64_e32 v[154:155], v[192:193]
	v_mov_b64_e32 v[156:157], v[194:195]
	v_mov_b64_e32 v[170:171], v[214:215]
	v_mov_b64_e32 v[172:173], v[216:217]
	s_waitcnt vmcnt(0) lgkmcnt(0)
	v_pk_fma_f32 v[168:169], s[4:5], v[76:77], v[154:155] neg_lo:[1,0,0] neg_hi:[1,0,0]
	s_nop 0
	v_pk_mul_f32 v[154:155], v[168:169], v[168:169]
	v_pk_fma_f32 v[164:165], s[4:5], v[78:79], v[156:157] neg_lo:[1,0,0] neg_hi:[1,0,0]
	v_add_f32_e32 v0, v0, v154
	v_add_f32_e32 v0, v155, v0
	v_pk_mul_f32 v[154:155], v[164:165], v[164:165]
	s_nop 0
	v_add_f32_e32 v0, v154, v0
	v_add_f32_e32 v0, v155, v0
	v_mov_b64_e32 v[154:155], v[210:211]
	v_mov_b64_e32 v[156:157], v[212:213]
	s_waitcnt vmcnt(0) lgkmcnt(0)
	v_pk_fma_f32 v[160:161], s[4:5], v[80:81], v[154:155] neg_lo:[1,0,0] neg_hi:[1,0,0]
	s_nop 0
	v_pk_mul_f32 v[154:155], v[160:161], v[160:161]
	v_pk_fma_f32 v[158:159], s[4:5], v[82:83], v[156:157] neg_lo:[1,0,0] neg_hi:[1,0,0]
	v_add_f32_e32 v0, v154, v0
	v_add_f32_e32 v0, v155, v0
	v_pk_mul_f32 v[154:155], v[158:159], v[158:159]
	v_pk_fma_f32 v[156:157], s[4:5], v[84:85], v[170:171] neg_lo:[1,0,0] neg_hi:[1,0,0]
	v_add_f32_e32 v0, v154, v0
	v_add_f32_e32 v0, v155, v0
	v_pk_mul_f32 v[154:155], v[156:157], v[156:157]
	s_nop 0
	v_add_f32_e32 v0, v154, v0
	v_add_f32_e32 v0, v155, v0
	v_pk_fma_f32 v[154:155], s[4:5], v[86:87], v[172:173] neg_lo:[1,0,0] neg_hi:[1,0,0]
	v_mov_b64_e32 v[170:171], v[218:219]
	v_mov_b64_e32 v[172:173], v[220:221]
	v_pk_mul_f32 v[162:163], v[154:155], v[154:155]
	s_waitcnt vmcnt(0) lgkmcnt(0)
	v_pk_fma_f32 v[166:167], s[4:5], v[90:91], v[172:173] neg_lo:[1,0,0] neg_hi:[1,0,0]
	v_add_f32_e32 v0, v162, v0
	v_add_f32_e32 v0, v163, v0
	v_pk_fma_f32 v[162:163], s[4:5], v[88:89], v[170:171] neg_lo:[1,0,0] neg_hi:[1,0,0]
	s_nop 0
	v_pk_mul_f32 v[94:95], v[162:163], v[162:163]
	s_nop 0
	v_add_f32_e32 v0, v94, v0
	v_add_f32_e32 v0, v95, v0
	v_pk_mul_f32 v[94:95], v[166:167], v[166:167]
	s_nop 0
	v_add_f32_e32 v0, v94, v0
	v_add_f32_e32 v0, v95, v0
	v_mov_b32_e32 v93, v0
	s_nop 1
	v_permlane32_swap_b32_e32 v0, v93
	v_add_f32_e32 v0, v0, v93
	v_fmamk_f32 v0, v0, 0x3c000000, v232
	v_cmp_gt_f32_e32 vcc, s0, v0
	v_mul_f32_e32 v93, 0x4b800000, v0
	s_nop 0
	v_cndmask_b32_e32 v0, v0, v93, vcc
	v_rsq_f32_e32 v0, v0
	s_nop 0
	v_mul_f32_e32 v93, 0x45800000, v0
	v_cndmask_b32_e32 v0, v0, v93, vcc
	v_mul_f32_e32 v170, v244, v0
